# attention: next V tile global loads issued after the K fragment loads (counted waits before QK cover K only)
# baseline (speedup 1.0000x reference)
; #define MFMA16(a, b, c) __builtin_amdgcn_mfma_f32_16x16x32_bf16((a), (b), (c), 0, 0, 0)
; DEVI void attn_item(const Params& p, int j, int h, int qt, float lam, float one_m_linit, char* smem) {
;     ...
;   auto gload = [&](int kt) {
;     const int k0 = kt * 64;
; #pragma unroll
;     for (int i = 0; i < 4; ++i) rv[i] = *(const u32x4*)(Vg + (size_t)(krow + i * 32) * LR + k0 + kkc * 8);
;     ...
;   for (int kt = 0; kt < nkt; ++kt) {
;     const char* b = smem + (kt & 1) * 34816;
;     if (kt + 1 < nkt) gload(kt + 1);
;     const int k0 = kt * 64;
;     if (k0 <= qw + 31) {
;       f32x4 st[2][4];
; #pragma unroll
;       for (int qi = 0; qi < 2; ++qi)
; #pragma unroll
;         for (int ki = 0; ki < 4; ++ki) st[qi][ki] = f32x4{-mrun[qi], -mrun[qi], -mrun[qi], -mrun[qi]};
;       const char* vb = b + 16384;
;       bf16x8 vf[2][4];
;       auto vload = [&](int g, int slot) {
; #pragma unroll
;         for (int dd = 0; dd < 2; ++dd)
; #pragma unroll
;           for (int s2 = 0; s2 < 2; ++s2) {
;             const char* a = vb + ((g * 2 + dd) * 16 + l15) * 144 + s2 * 64 + quad * 8;
;             vf[slot][dd * 2 + s2] = mk8(*(const u32x2*)a, *(const u32x2*)(a + 32));
;           }
;       };
;       __builtin_amdgcn_s_setprio(2);
; #pragma unroll
;       for (int ki = 0; ki < 4; ++ki)
; #pragma unroll
;         for (int ks = 0; ks < 2; ++ks) {
; #pragma unroll
;           for (int qi = 0; qi < 2; ++qi) st[qi][ki] = MFMA16(kf[ki][ks], qf[qi][ks], st[qi][ki]);
;         }
;       __builtin_amdgcn_s_setprio(0);
;       if (kt + 1 < nkt) kload(kt + 1);
.LBB0_166:
	v_cndmask_b32_e64 v138, 0, 1, s[0:1]
	v_cmp_le_i32_e32 vcc, s58, v238
	v_cmp_ne_u32_e64 s[42:43], 1, v138
	s_and_saveexec_b64 s[88:89], vcc
	s_cbranch_execz .LBB0_242
	v_xor_b32_e32 v138, 0x80000000, v237
	v_xor_b32_e32 v142, 0x80000000, v236
	v_mov_b32_e32 v139, v138
	v_mov_b32_e32 v140, v138
	v_mov_b32_e32 v141, v138
	v_mov_b32_e32 v143, v142
	v_mov_b32_e32 v144, v142
	v_mov_b32_e32 v145, v142
	s_setprio 2
	s_waitcnt vmcnt(7)
	v_mfma_f32_16x16x32_bf16 v[146:149], v[34:37], v[2:5], v[138:141]
	v_mfma_f32_16x16x32_bf16 v[150:153], v[34:37], v[18:21], v[142:145]
	s_waitcnt vmcnt(6)
	v_mfma_f32_16x16x32_bf16 v[166:169], v[38:41], v[6:9], v[146:149]
	s_waitcnt vmcnt(5)
	v_mfma_f32_16x16x32_bf16 v[146:149], v[42:45], v[2:5], v[138:141]
	v_mfma_f32_16x16x32_bf16 v[162:165], v[38:41], v[26:29], v[150:153]
	v_mfma_f32_16x16x32_bf16 v[150:153], v[42:45], v[18:21], v[142:145]
	s_waitcnt vmcnt(4)
	v_mfma_f32_16x16x32_bf16 v[158:161], v[46:49], v[6:9], v[146:149]
	s_waitcnt vmcnt(3)
	v_mfma_f32_16x16x32_bf16 v[146:149], v[50:53], v[2:5], v[138:141]
	v_mfma_f32_16x16x32_bf16 v[170:173], v[50:53], v[18:21], v[142:145]
	v_mfma_f32_16x16x32_bf16 v[154:157], v[46:49], v[26:29], v[150:153]
	s_waitcnt vmcnt(2)
	v_mfma_f32_16x16x32_bf16 v[150:153], v[54:57], v[6:9], v[146:149]
	v_mfma_f32_16x16x32_bf16 v[146:149], v[54:57], v[26:29], v[170:173]
	s_waitcnt vmcnt(1)
	v_mfma_f32_16x16x32_bf16 v[138:141], v[58:61], v[2:5], v[138:141]
	v_mfma_f32_16x16x32_bf16 v[170:173], v[58:61], v[18:21], v[142:145]
	s_waitcnt vmcnt(0)
	v_mfma_f32_16x16x32_bf16 v[142:145], v[62:65], v[6:9], v[138:141]
	v_mfma_f32_16x16x32_bf16 v[138:141], v[62:65], v[26:29], v[170:173]
	s_setprio 0
	s_and_b64 vcc, exec, s[42:43]
	s_cbranch_vccnz .LBB0_169
	s_add_i32 s0, s6, -7
	s_ashr_i32 s1, s0, 31
	s_lshl_b64 s[0:1], s[0:1], 10
	v_lshl_add_u64 v[34:35], v[196:197], 0, s[0:1]
	s_add_i32 s0, s6, -6
	s_ashr_i32 s1, s0, 31
	s_lshl_b64 s[0:1], s[0:1], 10
	v_lshl_add_u64 v[38:39], v[196:197], 0, s[0:1]
	s_add_i32 s0, s6, -5
	s_ashr_i32 s1, s0, 31
	s_lshl_b64 s[0:1], s[0:1], 10
	v_lshl_add_u64 v[42:43], v[196:197], 0, s[0:1]
	s_add_i32 s0, s6, -4
	s_ashr_i32 s1, s0, 31
	s_lshl_b64 s[0:1], s[0:1], 10
	v_lshl_add_u64 v[46:47], v[196:197], 0, s[0:1]
	s_add_i32 s0, s6, -3
	s_ashr_i32 s1, s0, 31
	s_lshl_b64 s[0:1], s[0:1], 10
	v_lshl_add_u64 v[50:51], v[196:197], 0, s[0:1]
	s_add_i32 s0, s6, -2
	s_ashr_i32 s1, s0, 31
	s_lshl_b64 s[0:1], s[0:1], 10
	v_lshl_add_u64 v[54:55], v[196:197], 0, s[0:1]
	s_add_i32 s0, s6, -1
	s_ashr_i32 s1, s0, 31
	s_lshl_b64 s[0:1], s[0:1], 10
	s_ashr_i32 s7, s6, 31
	v_lshl_add_u64 v[58:59], v[196:197], 0, s[0:1]
	s_lshl_b64 s[0:1], s[6:7], 10
	v_lshl_add_u64 v[62:63], v[196:197], 0, s[0:1]
	global_load_dwordx4 v[34:37], v[34:35], off
	s_nop 0
	global_load_dwordx4 v[38:41], v[38:39], off
	s_nop 0
	global_load_dwordx4 v[42:45], v[42:43], off
	s_nop 0
	global_load_dwordx4 v[46:49], v[46:47], off
	s_nop 0
	global_load_dwordx4 v[50:53], v[50:51], off
	s_nop 0
	global_load_dwordx4 v[54:57], v[54:55], off
	s_nop 0
	global_load_dwordx4 v[58:61], v[58:59], off
	s_nop 0
	global_load_dwordx4 v[62:65], v[62:63], off
	s_add_i32 s62, s58, 64
	s_lshl_b64 s[10:11], s[62:63], 1
	v_lshl_add_u64 v[10:11], v[198:199], 0, s[10:11]
	v_lshl_add_u64 v[14:15], v[200:201], 0, s[10:11]
	v_lshl_add_u64 v[22:23], v[202:203], 0, s[10:11]
	v_lshl_add_u64 v[30:31], v[204:205], 0, s[10:11]
	global_load_dwordx4 v[10:13], v[10:11], off
	s_nop 0
	global_load_dwordx4 v[14:17], v[14:15], off
	s_nop 0
	global_load_dwordx4 v[22:25], v[22:23], off
	s_nop 0
	global_load_dwordx4 v[30:33], v[30:31], off
